# gdn chain: loader waves issue the step-0/1 LDS-DMA requests when the workgroup enters the P2b->P3 grid barrier (blobs final one barrier earlier), in-place prologue keeps only its address set-up
# baseline (speedup 1.0000x reference)
; #define ISSUE_XG(s_) do { const unsigned char* g_ = A.blob + (unit0 + CHUNK_OF(s_)) * BLOB + lane * 16; const unsigned l_ = lds0 + ((s_) & 1) * C_BUF; \
;         _Pragma("unroll") for (int k = 0; k < 8; ++k) { const unsigned o_ = (lw + 4 * k) * 1024; DMA1(g_ + o_, l_ + o_); __builtin_amdgcn_s_sleep(LOADER_PACE); } } while (0)
; #define ISSUE_XG(s_) do { const unsigned char* g_ = A.blobA + (unit0 + CHUNK_OF(s_)) * BLOBA + qo + lane * 16; const unsigned l_ = lds0 + ((s_) & 1) * CB_BUF; \
;         _Pragma("unroll") for (int k = 0; k < 4; ++k) { const unsigned o_ = (lw + 4 * k) * 1024; DMA1(g_ + o_, l_ + o_); } } while (0)
; __device__ __forceinline__ void gdn_chain_unit(LAS unsigned char* lds, const GdnChainArgs& A, int item, int half) {
;     ...
;     if (w >= 4) {
;         const unsigned tbo = c ? B_TBB : B_TBF;
;     ...
;         if (!(flags & 4)) { ISSUE_XG(0); ISSUE_YG(0); ISSUE_XG(1); }
; __device__ __forceinline__ void xcd_barrier(const XcdBarrier& b) {
;     asm volatile("s_waitcnt vmcnt(0)" ::: "memory");
;     __syncthreads();
;     if (threadIdx.x == 0) {
;         unsigned* bar = b.bar;
;         __builtin_amdgcn_s_waitcnt(0);
;         unsigned nloc = b.st[0], nx = b.st[1];
;         if (nloc == 0u) { xcd_barrier_complete(bar, b.x, nloc, nx); b.st[0] = nloc; b.st[1] = nx; }
.LBB0_434:
	v_readlane_b32 s2, v254, 48
	v_readlane_b32 s86, v254, 18
	s_add_i32 s34, s2, 4
	v_readlane_b32 s87, v254, 19
	s_cmp_ge_i32 s34, s87
	s_cbranch_scc1 .LBB0_446
	s_waitcnt vmcnt(0)
	s_waitcnt vmcnt(0) lgkmcnt(0)
	s_barrier
	v_readlane_b32 s98, v251, 59
	v_readfirstlane_b32 s99, v0
	s_nop 0
	s_cmp_lg_u32 s98, 0
	s_cbranch_scc1 .Lgdn_early_done
	s_cmp_lt_u32 s99, 0x100
	s_cbranch_scc1 .Lgdn_early_done
	v_readlane_b32 s4, v253, 53
	v_readlane_b32 s5, v253, 54
	v_readlane_b32 s26, v252, 1
	v_readlane_b32 s27, v252, 2
	v_readlane_b32 s28, v253, 61
	s_lshr_b32 s29, s99, 6
	s_and_b32 s29, s29, 3
	s_lshl_b32 s30, s29, 10
	v_and_b32_e32 v8, 63, v0
	v_lshlrev_b32_e32 v8, 4, v8
	v_add_u32_e32 v8, s30, v8
	s_add_i32 s28, s28, 0xffff8000
	s_cmp_ge_u32 s29, 2
	s_cselect_b32 s31, s28, 0
	v_mov_b32_e32 v10, v8
	s_mov_b32 m0, s30
	s_nop 0
	global_load_lds_dwordx4 v8, s[4:5]
	v_add_u32_e32 v8, 0x1000, v8
	s_add_i32 m0, m0, 0x1000
	s_nop 0
	global_load_lds_dwordx4 v8, s[4:5]
	v_add_u32_e32 v8, 0x1000, v8
	s_add_i32 m0, m0, 0x1000
	s_nop 0
	global_load_lds_dwordx4 v8, s[4:5]
	v_add_u32_e32 v8, 0x1000, v8
	s_add_i32 m0, m0, 0x1000
	s_nop 0
	global_load_lds_dwordx4 v8, s[4:5]
	v_add_u32_e32 v8, 0x1000, v8
	s_add_i32 m0, m0, 0x1000
	s_nop 0
	global_load_lds_dwordx4 v8, s[4:5]
	v_add_u32_e32 v8, 0x1000, v8
	s_add_i32 m0, m0, 0x1000
	s_nop 0
	global_load_lds_dwordx4 v8, s[4:5]
	v_add_u32_e32 v8, 0x1000, v8
	s_add_i32 m0, m0, 0x1000
	s_nop 0
	global_load_lds_dwordx4 v8, s[4:5]
	v_add_u32_e32 v8, 0x1000, v8
	s_add_i32 m0, m0, 0x1000
	s_nop 0
	global_load_lds_dwordx4 v8, s[4:5]
	v_add_u32_e32 v8, 0x1000, v8
	s_add_i32 m0, m0, 0x1000
	s_nop 0
	global_load_lds_dwordx4 v8, s[4:5]
	v_add_u32_e32 v8, 0x1000, v8
	s_add_i32 m0, m0, 0x1000
	s_nop 0
	global_load_lds_dwordx4 v8, s[4:5]
	v_add_u32_e32 v8, 0x1000, v8
	s_add_i32 m0, m0, 0x1000
	s_nop 0
	global_load_lds_dwordx4 v8, s[4:5]
	v_add_u32_e32 v8, 0x1000, v8
	s_add_i32 m0, m0, 0x1000
	s_nop 0
	global_load_lds_dwordx4 v8, s[4:5]
	v_add_u32_e32 v8, 0x1000, v8
	v_add_u32_e32 v9, s31, v8
	s_add_i32 m0, m0, 0x1000
	s_nop 0
	global_load_lds_dwordx4 v9, s[4:5]
	v_add_u32_e32 v8, 0x1000, v8
	v_add_u32_e32 v9, s28, v8
	s_add_i32 m0, m0, 0x1000
	s_nop 0
	global_load_lds_dwordx4 v9, s[4:5]
	v_add_u32_e32 v8, 0x1000, v8
	v_add_u32_e32 v9, s28, v8
	s_add_i32 m0, m0, 0x1000
	s_nop 0
	global_load_lds_dwordx4 v9, s[4:5]
	v_add_u32_e32 v8, 0x1000, v8
	v_add_u32_e32 v9, s28, v8
	s_add_i32 m0, m0, 0x1000
	s_nop 0
	global_load_lds_dwordx4 v9, s[4:5]
	s_cmp_lt_u32 s29, 2
	s_cbranch_scc0 .Lgdn_early_x1
	v_add_u32_e32 v8, 0x1000, v8
	v_add_u32_e32 v9, s28, v8
	s_add_i32 m0, m0, 0x1000
	s_nop 0
	global_load_lds_dwordx4 v9, s[4:5]
.Lgdn_early_x1:
	s_add_i32 m0, s30, 0x10800
	s_nop 0
	global_load_lds_dwordx4 v10, s[26:27]
	v_add_u32_e32 v10, 0x1000, v10
	s_add_i32 m0, m0, 0x1000
	s_nop 0
	global_load_lds_dwordx4 v10, s[26:27]
	v_add_u32_e32 v10, 0x1000, v10
	s_add_i32 m0, m0, 0x1000
	s_nop 0
	global_load_lds_dwordx4 v10, s[26:27]
	v_add_u32_e32 v10, 0x1000, v10
	s_add_i32 m0, m0, 0x1000
	s_nop 0
	global_load_lds_dwordx4 v10, s[26:27]
	v_add_u32_e32 v10, 0x1000, v10
	s_add_i32 m0, m0, 0x1000
	s_nop 0
	global_load_lds_dwordx4 v10, s[26:27]
	v_add_u32_e32 v10, 0x1000, v10
	s_add_i32 m0, m0, 0x1000
	s_nop 0
	global_load_lds_dwordx4 v10, s[26:27]
	v_add_u32_e32 v10, 0x1000, v10
	s_add_i32 m0, m0, 0x1000
	s_nop 0
	global_load_lds_dwordx4 v10, s[26:27]
	v_add_u32_e32 v10, 0x1000, v10
	s_add_i32 m0, m0, 0x1000
	s_nop 0
	global_load_lds_dwordx4 v10, s[26:27]
.Lgdn_early_done:
	s_nop 0
	s_mov_b64 s[2:3], exec
	v_readlane_b32 s88, v254, 20
	v_readlane_b32 s89, v254, 21
	v_readlane_b32 s94, v254, 23
	v_readlane_b32 s72, v254, 25
	v_readlane_b32 s74, v254, 27
	v_readlane_b32 s76, v254, 29
	v_readlane_b32 s78, v254, 31
	v_readlane_b32 s80, v254, 33
	v_readlane_b32 s82, v254, 35
	v_readlane_b32 s68, v250, 26
	v_readlane_b32 s56, v254, 37
	v_readlane_b32 s52, v254, 44
	v_readlane_b32 s64, v254, 46
	v_readlane_b32 s42, v254, 55
	s_and_b64 s[4:5], s[2:3], s[88:89]
	v_readlane_b32 s85, v254, 16
	v_readlane_b32 s92, v254, 22
	v_readlane_b32 s95, v254, 24
	v_readlane_b32 s73, v254, 26
	v_readlane_b32 s75, v254, 28
	v_readlane_b32 s77, v254, 30
	v_readlane_b32 s79, v254, 32
	v_readlane_b32 s81, v254, 34
	v_readlane_b32 s83, v254, 36
	v_readlane_b32 s69, v250, 27
	v_readlane_b32 s57, v254, 38
	v_readlane_b32 s84, v254, 39
	v_readlane_b32 s58, v250, 28
	v_readlane_b32 s70, v254, 40
	v_readlane_b32 s71, v254, 41
	v_readlane_b32 s59, v254, 42
	v_readlane_b32 s60, v254, 43
	v_readlane_b32 s53, v254, 45
	v_readlane_b32 s65, v254, 47
	v_readlane_b32 s48, v254, 49
	v_readlane_b32 s43, v254, 56
	v_readlane_b32 s49, v254, 50
	s_mov_b64 exec, s[4:5]
	s_cbranch_execz .LBB0_488
	v_readlane_b32 s4, v252, 60
	s_waitcnt vmcnt(0) expcnt(0) lgkmcnt(0)
	s_nop 0
	v_mov_b32_e32 v2, s4
	ds_read_b32 v4, v2
	v_readlane_b32 s4, v252, 61
	s_waitcnt lgkmcnt(0)
	v_cmp_ne_u32_e32 vcc, 0, v4
	v_mov_b32_e32 v2, s4
	ds_read_b32 v2, v2
	s_cbranch_vccnz .LBB0_452
	v_readlane_b32 s6, v250, 8
	v_readlane_b32 s7, v250, 9
	s_load_dwordx2 s[4:5], s[6:7], 0x4
	s_mov_b32 s39, 1
	s_waitcnt lgkmcnt(0)
	s_mul_i32 s38, s4, s93
	s_mul_i32 s38, s38, s5
	s_branch .LBB0_439

; #define LBAR() do { asm volatile("s_waitcnt lgkmcnt(0)" ::: "memory"); __builtin_amdgcn_s_barrier(); asm volatile("" ::: "memory"); } while (0)
; #define WAITV(N_) asm volatile("s_waitcnt vmcnt(" #N_ ")" ::: "memory")
; #define ISSUE_XG(s_) do { const unsigned char* g_ = A.blob + (unit0 + CHUNK_OF(s_)) * BLOB + lane * 16; const unsigned l_ = lds0 + ((s_) & 1) * C_BUF; \
;         _Pragma("unroll") for (int k = 0; k < 8; ++k) { const unsigned o_ = (lw + 4 * k) * 1024; DMA1(g_ + o_, l_ + o_); __builtin_amdgcn_s_sleep(LOADER_PACE); } } while (0)
; #define WAITV(N_) asm volatile("s_waitcnt vmcnt(" #N_ ")" ::: "memory")
; #define ISSUE_XG(s_) do { const unsigned char* g_ = A.blobA + (unit0 + CHUNK_OF(s_)) * BLOBA + qo + lane * 16; const unsigned l_ = lds0 + ((s_) & 1) * CB_BUF; \
;         _Pragma("unroll") for (int k = 0; k < 4; ++k) { const unsigned o_ = (lw + 4 * k) * 1024; DMA1(g_ + o_, l_ + o_); } } while (0)
; __device__ __forceinline__ void gdn_chain_unit(LAS unsigned char* lds, const GdnChainArgs& A, int item, int half) {
;     ...
;     if (w >= 4) {
;         const unsigned tbo = c ? B_TBB : B_TBF;
;     ...
;         if (!(flags & 4)) { ISSUE_XG(0); ISSUE_YG(0); ISSUE_XG(1); }
;         WAITV(0);
;         LBAR();
.LBB0_655:
	s_and_b64 vcc, exec, s[2:3]
	s_cbranch_vccz .LBB0_667
	v_readlane_b32 s2, v253, 53
	v_readlane_b32 s3, v253, 54
	s_lshl_b32 s34, s62, 10
	s_or_b32 s4, s34, 0x1000
	v_lshl_add_u64 v[2:3], s[2:3], 0, v[130:131]
	s_add_i32 s2, s34, 0
	v_lshl_add_u64 v[4:5], v[2:3], 0, s[34:35]
	s_mov_b32 s5, s35
	s_add_i32 s2, s4, 0
	s_or_b32 s6, s34, 0x2000
	s_nop 0
	v_lshl_add_u64 v[4:5], v[2:3], 0, s[4:5]
	s_mov_b32 s7, s35
	s_add_i32 s2, s6, 0
	s_or_b32 s36, s34, 0x3000
	s_nop 0
	v_lshl_add_u64 v[4:5], v[2:3], 0, s[6:7]
	s_mov_b32 s37, s35
	s_add_i32 s2, s36, 0
	s_or_b32 s38, s34, 0x4000
	s_nop 0
	v_lshl_add_u64 v[4:5], v[2:3], 0, s[36:37]
	s_mov_b32 s39, s35
	s_add_i32 s2, s38, 0
	s_or_b32 s40, s34, 0x5000
	s_nop 0
	v_lshl_add_u64 v[4:5], v[2:3], 0, s[38:39]
	s_mov_b32 s41, s35
	s_add_i32 s2, s40, 0
	s_or_b32 s42, s34, 0x6000
	s_nop 0
	v_lshl_add_u64 v[4:5], v[2:3], 0, s[40:41]
	s_mov_b32 s43, s35
	s_add_i32 s2, s42, 0
	s_or_b32 s44, s34, 0x7000
	s_nop 0
	v_lshl_add_u64 v[4:5], v[2:3], 0, s[42:43]
	s_mov_b32 s45, s35
	s_add_i32 s2, s44, 0
	s_or_b32 s46, s34, 0x8000
	s_nop 0
	v_lshl_add_u64 v[4:5], v[2:3], 0, s[44:45]
	s_mov_b32 s47, s35
	s_add_i32 s2, s46, 0
	s_or_b32 s48, s34, 0x9000
	s_nop 0
	v_lshl_add_u64 v[4:5], v[2:3], 0, s[46:47]
	s_mov_b32 s49, s35
	s_add_i32 s2, s48, 0
	s_or_b32 s50, s34, 0xa000
	s_nop 0
	v_lshl_add_u64 v[4:5], v[2:3], 0, s[48:49]
	s_mov_b32 s51, s35
	s_add_i32 s2, s50, 0
	s_or_b32 s52, s34, 0xb000
	s_nop 0
	v_lshl_add_u64 v[4:5], v[2:3], 0, s[50:51]
	s_mov_b32 s53, s35
	s_add_i32 s2, s52, 0
	s_nop 0
	v_lshl_add_u64 v[4:5], v[2:3], 0, s[52:53]
	s_or_b32 s2, s62, 16
	s_lshl_b32 s3, s2, 10
	v_readlane_b32 s54, v253, 61
	s_or_b32 s67, s3, 0x8000
	s_add_i32 s3, s3, s54
	s_cmp_lt_u32 s2, 18
	s_cselect_b32 s54, s67, s3
	s_mov_b32 s55, s35
	s_add_i32 s2, s67, 0
	s_nop 0
	v_lshl_add_u64 v[4:5], v[2:3], 0, s[54:55]
	s_or_b32 s72, s34, 0xd000
	v_readlane_b32 s2, v253, 59
	s_or_b32 s56, s2, s34
	s_mov_b32 s57, s35
	s_add_i32 s2, s72, 0
	s_nop 0
	v_lshl_add_u64 v[4:5], v[2:3], 0, s[56:57]
	s_or_b32 s73, s34, 0xe000
	v_readlane_b32 s2, v253, 60
	s_or_b32 s58, s2, s34
	s_mov_b32 s59, s35
	s_add_i32 s2, s73, 0
	s_nop 0
	v_lshl_add_u64 v[4:5], v[2:3], 0, s[58:59]
	s_or_b32 s74, s34, 0xf000
	v_readlane_b32 s2, v253, 62
	s_or_b32 s60, s2, s34
	s_mov_b32 s61, s35
	s_add_i32 s2, s74, 0
	s_nop 0
	v_lshl_add_u64 v[4:5], v[2:3], 0, s[60:61]
	s_or_b32 s2, s62, 32
	s_cmp_lt_u32 s2, 34
	s_cselect_b64 s[64:65], -1, 0
	s_lshl_b32 s75, s2, 10
	s_mov_b64 s[2:3], -1
	s_and_b64 vcc, exec, s[64:65]
	s_nop 0
	s_cbranch_vccnz .LBB0_658
	v_readlane_b32 s2, v253, 61
	s_add_i32 s62, s75, s2
	s_mov_b32 s63, s35
	s_mov_b64 s[2:3], 0
.LBB0_658:
	s_mov_b64 s[70:71], s[94:95]
	s_andn2_b64 vcc, exec, s[2:3]
	s_cbranch_vccnz .LBB0_660
	v_readlane_b32 s3, v253, 61
	s_add_i32 s2, s75, 0
	s_add_i32 s62, s75, s3
	s_mov_b32 s63, s35
	s_add_i32 s2, s2, 0x8000
	v_lshl_add_u64 v[2:3], v[2:3], 0, s[62:63]
	s_nop 0
.LBB0_660:
	v_readlane_b32 s2, v252, 1
	v_readlane_b32 s3, v252, 2
	s_add_i32 s76, 0, 0x10800
	v_readlane_b32 vcc_lo, v254, 44
	v_lshl_add_u64 v[2:3], s[2:3], 0, v[130:131]
	s_add_i32 s2, s34, s76
	v_lshl_add_u64 v[4:5], v[2:3], 0, s[34:35]
	s_add_i32 s2, s4, s76
	s_nop 0
	v_lshl_add_u64 v[4:5], v[2:3], 0, s[4:5]
	s_add_i32 s2, s6, s76
	s_nop 0
	v_lshl_add_u64 v[4:5], v[2:3], 0, s[6:7]
	s_add_i32 s2, s36, s76
	s_nop 0
	v_lshl_add_u64 v[4:5], v[2:3], 0, s[36:37]
	s_add_i32 s2, s38, s76
	s_nop 0
	v_lshl_add_u64 v[4:5], v[2:3], 0, s[38:39]
	s_add_i32 s2, s40, s76
	s_nop 0
	v_lshl_add_u64 v[4:5], v[2:3], 0, s[40:41]
	s_add_i32 s2, s42, s76
	s_nop 0
	v_lshl_add_u64 v[4:5], v[2:3], 0, s[42:43]
	s_nop 0
	v_lshl_add_u64 v[2:3], v[2:3], 0, s[44:45]
	s_add_i32 s2, s44, s76
	s_nop 0
	s_waitcnt vmcnt(0)
	s_waitcnt lgkmcnt(0)
	s_barrier
	v_readlane_b32 s2, v253, 63
	v_readlane_b32 s3, v252, 0
	v_readlane_b32 s94, v254, 46
	s_add_i32 s77, s75, 0x8000
	v_lshl_add_u64 v[2:3], s[2:3], 0, v[130:131]
	s_mov_b32 s80, 0
	s_mov_b32 s78, 30
	v_readlane_b32 vcc_hi, v254, 45
	v_readlane_b32 s95, v254, 47
	s_branch .LBB0_662
